# MLA latent attention: tile-1 softmax and PV deferred across the step barrier (overlap the next step's QK), tile-1 V fragments register-resident; QK1 interleaved with softmax0
# baseline (speedup 1.0000x reference)
.LBB0_786:
	s_bitcmp1_b32 s2, 0
	s_cselect_b32 s2, 0xa000, 0
	v_add_u32_e32 v96, s2, v95
	ds_read_b128 v[172:175], v96
	ds_read_b128 v[176:179], v96 offset:1024
	ds_read_b128 v[188:191], v96 offset:2048
	ds_read_b128 v[192:195], v96 offset:3072
	ds_read_b128 v[198:201], v96 offset:4096
	ds_read_b128 v[202:205], v96 offset:5120
	s_cmp_eq_u32 s5, 1
	s_cbranch_scc1 .Lmy_first
	s_waitcnt lgkmcnt(5)
	v_mfma_f32_32x32x16_bf16 v[64:79], v[172:175], v[82:85], 0
	ds_read_b128 v[172:175], v96 offset:6144
	s_waitcnt lgkmcnt(5)
	v_mfma_f32_32x32x16_bf16 v[64:79], v[176:179], v[86:89], v[64:79]
	ds_read_b128 v[176:179], v96 offset:7168
	v_max_f32_e32 v111, v219, v219
	v_max_f32_e32 v159, v218, v218
	v_max_f32_e32 v111, v159, v111
	v_max3_f32 v111, v111, v220, v221
	v_max3_f32 v111, v111, v222, v223
	v_max3_f32 v111, v111, v224, v225
	v_max3_f32 v111, v111, v226, v227
	v_max3_f32 v111, v111, v228, v229
	v_max3_f32 v111, v111, v230, v231
	v_max3_f32 v111, v111, v232, v233
	v_mov_b32_e32 v159, v111
	s_nop 1
	v_permlane32_swap_b32_e32 v111, v159
	v_max_f32_e32 v159, v159, v159
	v_max_f32_e32 v111, v111, v111
	v_max_f32_e32 v111, v111, v159
	v_mul_f32_e32 v111, 0x3dd53b94, v111
	v_cmp_le_f32_e32 vcc, v111, v110
	s_cmp_eq_u64 vcc, exec
	s_cbranch_scc1 .LBB0_790
	v_max_f32_e32 v110, v111, v111
	v_max_f32_e32 v111, v80, v80
	v_max_f32_e32 v111, v111, v110
	v_sub_f32_e32 v80, v80, v111
	v_exp_f32_e32 v80, v80
	v_xor_b32_e32 v110, 0x80000000, v111
	v_mul_f32_e32 v81, v81, v80
	v_pk_mul_f32 v[62:63], v[62:63], v[80:81] op_sel_hi:[1,0]
	v_pk_mul_f32 v[60:61], v[60:61], v[80:81] op_sel_hi:[1,0]
	v_pk_mul_f32 v[58:59], v[58:59], v[80:81] op_sel_hi:[1,0]
	v_pk_mul_f32 v[56:57], v[56:57], v[80:81] op_sel_hi:[1,0]
	v_pk_mul_f32 v[54:55], v[54:55], v[80:81] op_sel_hi:[1,0]
	v_pk_mul_f32 v[52:53], v[52:53], v[80:81] op_sel_hi:[1,0]
	v_pk_mul_f32 v[50:51], v[50:51], v[80:81] op_sel_hi:[1,0]
	v_pk_mul_f32 v[48:49], v[48:49], v[80:81] op_sel_hi:[1,0]
	v_pk_mul_f32 v[46:47], v[46:47], v[80:81] op_sel_hi:[1,0]
	v_pk_mul_f32 v[44:45], v[44:45], v[80:81] op_sel_hi:[1,0]
	v_pk_mul_f32 v[42:43], v[42:43], v[80:81] op_sel_hi:[1,0]
	v_pk_mul_f32 v[40:41], v[40:41], v[80:81] op_sel_hi:[1,0]
	v_pk_mul_f32 v[38:39], v[38:39], v[80:81] op_sel_hi:[1,0]
	v_pk_mul_f32 v[36:37], v[36:37], v[80:81] op_sel_hi:[1,0]
	v_pk_mul_f32 v[34:35], v[34:35], v[80:81] op_sel_hi:[1,0]
	v_pk_mul_f32 v[32:33], v[32:33], v[80:81] op_sel_hi:[1,0]
	v_pk_mul_f32 v[30:31], v[30:31], v[80:81] op_sel_hi:[1,0]
	v_pk_mul_f32 v[28:29], v[28:29], v[80:81] op_sel_hi:[1,0]
	v_pk_mul_f32 v[26:27], v[26:27], v[80:81] op_sel_hi:[1,0]
	v_pk_mul_f32 v[24:25], v[24:25], v[80:81] op_sel_hi:[1,0]
	v_pk_mul_f32 v[22:23], v[22:23], v[80:81] op_sel_hi:[1,0]
	v_pk_mul_f32 v[20:21], v[20:21], v[80:81] op_sel_hi:[1,0]
	v_pk_mul_f32 v[18:19], v[18:19], v[80:81] op_sel_hi:[1,0]
	v_pk_mul_f32 v[16:17], v[16:17], v[80:81] op_sel_hi:[1,0]
	v_pk_mul_f32 v[14:15], v[14:15], v[80:81] op_sel_hi:[1,0]
	v_pk_mul_f32 v[12:13], v[12:13], v[80:81] op_sel_hi:[1,0]
	v_pk_mul_f32 v[10:11], v[10:11], v[80:81] op_sel_hi:[1,0]
	v_pk_mul_f32 v[8:9], v[8:9], v[80:81] op_sel_hi:[1,0]
	v_pk_mul_f32 v[6:7], v[6:7], v[80:81] op_sel_hi:[1,0]
	v_pk_mul_f32 v[4:5], v[4:5], v[80:81] op_sel_hi:[1,0]
	v_pk_mul_f32 v[2:3], v[2:3], v[80:81] op_sel_hi:[1,0]
	v_pk_mul_f32 v[0:1], v[0:1], v[80:81] op_sel_hi:[1,0]
	v_mov_b32_e32 v80, v111
	s_branch .LBB0_791

.LBB0_791:
	s_waitcnt lgkmcnt(5)
	v_mfma_f32_32x32x16_bf16 v[64:79], v[188:191], v[90:93], v[64:79]
	ds_read_b128 v[188:191], v96 offset:8192
	v_fmamk_f32 v218, v218, 0x3dd53b94, v110
	v_exp_f32_e32 v218, v218
	v_fmamk_f32 v219, v219, 0x3dd53b94, v110
	v_exp_f32_e32 v219, v219
	v_fmamk_f32 v220, v220, 0x3dd53b94, v110
	v_exp_f32_e32 v220, v220
	s_waitcnt lgkmcnt(5)
	v_mfma_f32_32x32x16_bf16 v[64:79], v[192:195], v[112:115], v[64:79]
	ds_read_b128 v[192:195], v96 offset:9216
	v_fmamk_f32 v221, v221, 0x3dd53b94, v110
	v_exp_f32_e32 v221, v221
	v_fmamk_f32 v222, v222, 0x3dd53b94, v110
	v_add_f32_e32 v111, 0, v218
	v_exp_f32_e32 v222, v222
	v_fmamk_f32 v223, v223, 0x3dd53b94, v110
	s_waitcnt lgkmcnt(5)
	v_mfma_f32_32x32x16_bf16 v[64:79], v[198:201], v[116:119], v[64:79]
	ds_read_b128 v[198:201], v96 offset:10240
	v_add_f32_e32 v111, v219, v111
	v_exp_f32_e32 v223, v223
	v_fmamk_f32 v224, v224, 0x3dd53b94, v110
	v_add_f32_e32 v111, v220, v111
	v_exp_f32_e32 v224, v224
	v_fmamk_f32 v225, v225, 0x3dd53b94, v110
	s_waitcnt lgkmcnt(5)
	v_mfma_f32_32x32x16_bf16 v[64:79], v[202:205], v[120:123], v[64:79]
	ds_read_b128 v[202:205], v96 offset:11264
	v_add_f32_e32 v111, v221, v111
	v_exp_f32_e32 v225, v225
	v_fmamk_f32 v226, v226, 0x3dd53b94, v110
	v_add_f32_e32 v111, v222, v111
	v_exp_f32_e32 v159, v226
	v_add_f32_e32 v111, v223, v111
	s_waitcnt lgkmcnt(5)
	v_mfma_f32_32x32x16_bf16 v[64:79], v[172:175], v[124:127], v[64:79]
	ds_read_b128 v[172:175], v96 offset:20480
	v_add_f32_e32 v111, v224, v111
	v_add_f32_e32 v111, v225, v111
	v_fmamk_f32 v227, v227, 0x3dd53b94, v110
	v_add_f32_e32 v226, v159, v111
	v_exp_f32_e32 v111, v227
	v_fmamk_f32 v227, v228, 0x3dd53b94, v110
	s_waitcnt lgkmcnt(5)
	v_mfma_f32_32x32x16_bf16 v[64:79], v[176:179], v[128:131], v[64:79]
	ds_read_b128 v[176:179], v96 offset:21504
	v_exp_f32_e32 v165, v227
	v_fmamk_f32 v227, v229, 0x3dd53b94, v110
	v_exp_f32_e32 v166, v227
	v_fmamk_f32 v227, v230, 0x3dd53b94, v110
	v_exp_f32_e32 v167, v227
	v_fmamk_f32 v227, v231, 0x3dd53b94, v110
	s_waitcnt lgkmcnt(5)
	v_mfma_f32_32x32x16_bf16 v[64:79], v[188:191], v[132:135], v[64:79]
	ds_read_b128 v[188:191], v96 offset:22528
	v_add_f32_e32 v226, v111, v226
	v_exp_f32_e32 v168, v227
	v_fmamk_f32 v227, v232, 0x3dd53b94, v110
	v_add_f32_e32 v226, v165, v226
	v_exp_f32_e32 v169, v227
	v_fmac_f32_e32 v110, 0x3dd53b94, v233
	s_waitcnt lgkmcnt(5)
	v_mfma_f32_32x32x16_bf16 v[64:79], v[192:195], v[136:139], v[64:79]
	ds_read_b128 v[192:195], v96 offset:23552
	v_add_f32_e32 v226, v166, v226
	v_exp_f32_e32 v110, v110
	v_add_f32_e32 v226, v167, v226
	v_add_f32_e32 v226, v168, v226
	v_add_f32_e32 v226, v169, v226
	v_add_f32_e32 v226, v110, v226
	s_waitcnt lgkmcnt(5)
	v_mfma_f32_32x32x16_bf16 v[64:79], v[198:201], v[140:143], v[64:79]
	ds_read_b128 v[198:201], v96 offset:24576
	v_cvt_pk_bf16_f32 v218, v218, v219
	v_cvt_pk_bf16_f32 v219, v220, v221
	v_cvt_pk_bf16_f32 v220, v222, v223
	v_cvt_pk_bf16_f32 v221, v224, v225
	v_mov_b32_e32 v227, v226
	s_nop 1
	s_waitcnt lgkmcnt(5)
	v_mfma_f32_32x32x16_bf16 v[64:79], v[202:205], v[144:147], v[64:79]
	ds_read_b128 v[202:205], v96 offset:25600
	v_permlane32_swap_b32_e32 v226, v227
	v_add_f32_e32 v226, v226, v227
	v_add_f32_e32 v81, v81, v226
	v_mfma_f32_32x32x16_bf16 v[48:63], v[148:151], v[218:221], v[48:63]
	ds_read_b128 v[148:151], v96 offset:12288
	v_mfma_f32_32x32x16_bf16 v[32:47], v[106:109], v[218:221], v[32:47]
	ds_read_b128 v[106:109], v96 offset:13312
	v_mfma_f32_32x32x16_bf16 v[16:31], v[98:101], v[218:221], v[16:31]
	v_cvt_pk_bf16_f32 v98, v159, v111
	v_cvt_pk_bf16_f32 v99, v165, v166
	v_cvt_pk_bf16_f32 v100, v167, v168
	v_cvt_pk_bf16_f32 v101, v169, v110
	v_mfma_f32_32x32x16_bf16 v[0:15], v[102:105], v[218:221], v[0:15]
	ds_read_b128 v[102:105], v96 offset:15360
	v_mfma_f32_32x32x16_bf16 v[48:63], v[234:237], v[98:101], v[48:63]
	v_mfma_f32_32x32x16_bf16 v[32:47], v[206:209], v[98:101], v[32:47]
	v_mfma_f32_32x32x16_bf16 v[16:31], v[238:241], v[98:101], v[16:31]
	v_mfma_f32_32x32x16_bf16 v[0:15], v[242:245], v[98:101], v[0:15]
	ds_read_b128 v[98:101], v96 offset:14336
	s_branch .Lmy_join
.Lmy_first:
	s_waitcnt lgkmcnt(5)
	v_mfma_f32_32x32x16_bf16 v[64:79], v[172:175], v[82:85], 0
	ds_read_b128 v[172:175], v96 offset:6144
	s_waitcnt lgkmcnt(5)
	v_mfma_f32_32x32x16_bf16 v[64:79], v[176:179], v[86:89], v[64:79]
	ds_read_b128 v[176:179], v96 offset:7168
	s_waitcnt lgkmcnt(5)
	v_mfma_f32_32x32x16_bf16 v[64:79], v[188:191], v[90:93], v[64:79]
	ds_read_b128 v[188:191], v96 offset:8192
	s_waitcnt lgkmcnt(5)
	v_mfma_f32_32x32x16_bf16 v[64:79], v[192:195], v[112:115], v[64:79]
	ds_read_b128 v[192:195], v96 offset:9216
	s_waitcnt lgkmcnt(5)
	v_mfma_f32_32x32x16_bf16 v[64:79], v[198:201], v[116:119], v[64:79]
	ds_read_b128 v[198:201], v96 offset:10240
	s_waitcnt lgkmcnt(5)
	v_mfma_f32_32x32x16_bf16 v[64:79], v[202:205], v[120:123], v[64:79]
	ds_read_b128 v[202:205], v96 offset:11264
	s_waitcnt lgkmcnt(5)
	v_mfma_f32_32x32x16_bf16 v[64:79], v[172:175], v[124:127], v[64:79]
	ds_read_b128 v[172:175], v96 offset:20480
	s_waitcnt lgkmcnt(5)
	v_mfma_f32_32x32x16_bf16 v[64:79], v[176:179], v[128:131], v[64:79]
	ds_read_b128 v[176:179], v96 offset:21504
	s_waitcnt lgkmcnt(5)
	v_mfma_f32_32x32x16_bf16 v[64:79], v[188:191], v[132:135], v[64:79]
	ds_read_b128 v[188:191], v96 offset:22528
	s_waitcnt lgkmcnt(5)
	v_mfma_f32_32x32x16_bf16 v[64:79], v[192:195], v[136:139], v[64:79]
	ds_read_b128 v[192:195], v96 offset:23552
	s_waitcnt lgkmcnt(5)
	v_mfma_f32_32x32x16_bf16 v[64:79], v[198:201], v[140:143], v[64:79]
	ds_read_b128 v[198:201], v96 offset:24576
	s_waitcnt lgkmcnt(5)
	v_mfma_f32_32x32x16_bf16 v[64:79], v[202:205], v[144:147], v[64:79]
	ds_read_b128 v[202:205], v96 offset:25600
	ds_read_b128 v[148:151], v96 offset:12288
	ds_read_b128 v[106:109], v96 offset:13312
	ds_read_b128 v[102:105], v96 offset:15360
	ds_read_b128 v[98:101], v96 offset:14336
.Lmy_join:
	s_waitcnt lgkmcnt(9)
	v_mfma_f32_32x32x16_bf16 v[218:233], v[172:175], v[82:85], 0
	ds_read_b128 v[172:175], v96 offset:26624
	s_waitcnt lgkmcnt(9)
	v_mfma_f32_32x32x16_bf16 v[218:233], v[176:179], v[86:89], v[218:233]
	ds_read_b128 v[176:179], v96 offset:27648
	s_nop 3
	v_max_f32_e32 v110, v65, v65
	v_max_f32_e32 v111, v64, v64
	v_max_f32_e32 v110, v111, v110
	v_max3_f32 v110, v110, v66, v67
	v_max3_f32 v110, v110, v68, v69
	v_max3_f32 v110, v110, v70, v71
	v_max3_f32 v110, v110, v72, v73
	v_max3_f32 v110, v110, v74, v75
	v_max3_f32 v110, v110, v76, v77
	v_max3_f32 v110, v110, v78, v79
	v_mov_b32_e32 v111, v110
	s_nop 1
	v_permlane32_swap_b32_e32 v110, v111
	v_max_f32_e32 v111, v111, v111
	v_max_f32_e32 v110, v110, v110
	v_max_f32_e32 v110, v110, v111
	v_mul_f32_e32 v111, 0x3dd53b94, v110
	v_add_f32_e32 v110, 0x41000000, v80
	v_cmp_le_f32_e32 vcc, v111, v110
	s_cmp_eq_u64 vcc, exec
	s_cbranch_scc1 .LBB0_788
	v_max_f32_e32 v110, v111, v111
	v_max_f32_e32 v111, v80, v80
	v_max_f32_e32 v111, v111, v110
	v_sub_f32_e32 v80, v80, v111
	v_exp_f32_e32 v80, v80
	v_add_f32_e32 v110, 0x41000000, v111
	v_mul_f32_e32 v81, v81, v80
	v_pk_mul_f32 v[62:63], v[62:63], v[80:81] op_sel_hi:[1,0]
	v_pk_mul_f32 v[60:61], v[60:61], v[80:81] op_sel_hi:[1,0]
	v_pk_mul_f32 v[58:59], v[58:59], v[80:81] op_sel_hi:[1,0]
	v_pk_mul_f32 v[56:57], v[56:57], v[80:81] op_sel_hi:[1,0]
	v_pk_mul_f32 v[54:55], v[54:55], v[80:81] op_sel_hi:[1,0]
	v_pk_mul_f32 v[52:53], v[52:53], v[80:81] op_sel_hi:[1,0]
	v_pk_mul_f32 v[50:51], v[50:51], v[80:81] op_sel_hi:[1,0]
	v_pk_mul_f32 v[48:49], v[48:49], v[80:81] op_sel_hi:[1,0]
	v_pk_mul_f32 v[46:47], v[46:47], v[80:81] op_sel_hi:[1,0]
	v_pk_mul_f32 v[44:45], v[44:45], v[80:81] op_sel_hi:[1,0]
	v_pk_mul_f32 v[42:43], v[42:43], v[80:81] op_sel_hi:[1,0]
	v_pk_mul_f32 v[40:41], v[40:41], v[80:81] op_sel_hi:[1,0]
	v_pk_mul_f32 v[38:39], v[38:39], v[80:81] op_sel_hi:[1,0]
	v_pk_mul_f32 v[36:37], v[36:37], v[80:81] op_sel_hi:[1,0]
	v_pk_mul_f32 v[34:35], v[34:35], v[80:81] op_sel_hi:[1,0]
	v_pk_mul_f32 v[32:33], v[32:33], v[80:81] op_sel_hi:[1,0]
	v_pk_mul_f32 v[30:31], v[30:31], v[80:81] op_sel_hi:[1,0]
	v_pk_mul_f32 v[28:29], v[28:29], v[80:81] op_sel_hi:[1,0]
	v_pk_mul_f32 v[26:27], v[26:27], v[80:81] op_sel_hi:[1,0]
	v_pk_mul_f32 v[24:25], v[24:25], v[80:81] op_sel_hi:[1,0]
	v_pk_mul_f32 v[22:23], v[22:23], v[80:81] op_sel_hi:[1,0]
	v_pk_mul_f32 v[20:21], v[20:21], v[80:81] op_sel_hi:[1,0]
	v_pk_mul_f32 v[18:19], v[18:19], v[80:81] op_sel_hi:[1,0]
	v_pk_mul_f32 v[16:17], v[16:17], v[80:81] op_sel_hi:[1,0]
	v_pk_mul_f32 v[14:15], v[14:15], v[80:81] op_sel_hi:[1,0]
	v_pk_mul_f32 v[12:13], v[12:13], v[80:81] op_sel_hi:[1,0]
	v_pk_mul_f32 v[10:11], v[10:11], v[80:81] op_sel_hi:[1,0]
	v_pk_mul_f32 v[8:9], v[8:9], v[80:81] op_sel_hi:[1,0]
	v_pk_mul_f32 v[6:7], v[6:7], v[80:81] op_sel_hi:[1,0]
	v_pk_mul_f32 v[4:5], v[4:5], v[80:81] op_sel_hi:[1,0]
	v_pk_mul_f32 v[2:3], v[2:3], v[80:81] op_sel_hi:[1,0]
	v_pk_mul_f32 v[0:1], v[0:1], v[80:81] op_sel_hi:[1,0]
	v_mov_b32_e32 v80, v111
.LBB0_788:
	s_waitcnt lgkmcnt(9)
	v_mfma_f32_32x32x16_bf16 v[218:233], v[188:191], v[90:93], v[218:233]
	ds_read_b128 v[188:191], v96 offset:28672
	v_fma_f32 v64, v64, s80, -v80
	v_exp_f32_e32 v64, v64
	v_fma_f32 v65, v65, s80, -v80
	v_exp_f32_e32 v65, v65
	v_fma_f32 v66, v66, s80, -v80
	v_exp_f32_e32 v66, v66
	s_waitcnt lgkmcnt(9)
	v_mfma_f32_32x32x16_bf16 v[218:233], v[192:195], v[112:115], v[218:233]
	ds_read_b128 v[192:195], v96 offset:29696
	v_fma_f32 v67, v67, s80, -v80
	v_exp_f32_e32 v67, v67
	v_fma_f32 v68, v68, s80, -v80
	v_add_f32_e32 v111, 0, v64
	v_exp_f32_e32 v68, v68
	v_fma_f32 v69, v69, s80, -v80
	s_waitcnt lgkmcnt(9)
	v_mfma_f32_32x32x16_bf16 v[218:233], v[198:201], v[116:119], v[218:233]
	ds_read_b128 v[198:201], v96 offset:30720
	v_add_f32_e32 v111, v65, v111
	v_exp_f32_e32 v69, v69
	v_fma_f32 v70, v70, s80, -v80
	v_add_f32_e32 v111, v66, v111
	v_exp_f32_e32 v70, v70
	v_fma_f32 v71, v71, s80, -v80
	s_waitcnt lgkmcnt(9)
	v_mfma_f32_32x32x16_bf16 v[218:233], v[202:205], v[120:123], v[218:233]
	ds_read_b128 v[202:205], v96 offset:31744
	v_add_f32_e32 v111, v67, v111
	v_exp_f32_e32 v71, v71
	v_fma_f32 v72, v72, s80, -v80
	v_add_f32_e32 v111, v68, v111
	v_exp_f32_e32 v159, v72
	v_add_f32_e32 v111, v69, v111
	s_waitcnt lgkmcnt(5)
	v_mfma_f32_32x32x16_bf16 v[218:233], v[172:175], v[124:127], v[218:233]
	v_add_f32_e32 v111, v70, v111
	v_add_f32_e32 v111, v71, v111
	v_fma_f32 v73, v73, s80, -v80
	v_add_f32_e32 v72, v159, v111
	v_exp_f32_e32 v111, v73
	v_fma_f32 v73, v74, s80, -v80
	s_waitcnt lgkmcnt(4)
	v_mfma_f32_32x32x16_bf16 v[218:233], v[176:179], v[128:131], v[218:233]
	v_exp_f32_e32 v165, v73
	v_fma_f32 v73, v75, s80, -v80
	v_exp_f32_e32 v166, v73
	v_fma_f32 v73, v76, s80, -v80
	v_exp_f32_e32 v167, v73
	v_fma_f32 v73, v77, s80, -v80
	s_waitcnt lgkmcnt(3)
	v_mfma_f32_32x32x16_bf16 v[218:233], v[188:191], v[132:135], v[218:233]
	v_add_f32_e32 v72, v111, v72
	v_exp_f32_e32 v168, v73
	v_fma_f32 v73, v78, s80, -v80
	v_add_f32_e32 v72, v165, v72
	v_exp_f32_e32 v169, v73
	v_fma_f32 v73, v79, s80, -v80
	s_waitcnt lgkmcnt(2)
	v_mfma_f32_32x32x16_bf16 v[218:233], v[192:195], v[136:139], v[218:233]
	v_add_f32_e32 v72, v166, v72
	v_exp_f32_e32 v170, v73
	v_add_f32_e32 v72, v167, v72
	v_cvt_pk_bf16_f32 v64, v64, v65
	v_cvt_pk_bf16_f32 v65, v66, v67
	v_cvt_pk_bf16_f32 v66, v68, v69
	s_waitcnt lgkmcnt(1)
	v_mfma_f32_32x32x16_bf16 v[218:233], v[198:201], v[140:143], v[218:233]
	v_cvt_pk_bf16_f32 v67, v70, v71
	v_add_f32_e32 v72, v168, v72
	v_add_f32_e32 v72, v169, v72
	v_add_f32_e32 v72, v170, v72
	v_mov_b32_e32 v73, v72
	s_nop 1
	s_waitcnt lgkmcnt(0)
	v_mfma_f32_32x32x16_bf16 v[218:233], v[202:205], v[144:147], v[218:233]
	v_permlane32_swap_b32_e32 v72, v73
	v_add_f32_e32 v72, v72, v73
	v_add_f32_e32 v81, v81, v72
	s_waitcnt lgkmcnt(9)
	v_mfma_f32_32x32x16_bf16 v[48:63], v[148:151], v[64:67], v[48:63]
	ds_read_b128 v[234:237], v96 offset:16384
	ds_read_b128 v[68:71], v96 offset:17408
	ds_read_b128 v[72:75], v96 offset:18432
	ds_read_b128 v[76:79], v96 offset:19456
	ds_read_b128 v[148:151], v96 offset:32768
	s_waitcnt lgkmcnt(13)
	v_mfma_f32_32x32x16_bf16 v[32:47], v[106:109], v[64:67], v[32:47]
	ds_read_b128 v[106:109], v96 offset:33792
	s_waitcnt lgkmcnt(12)
	v_mfma_f32_32x32x16_bf16 v[16:31], v[98:101], v[64:67], v[16:31]
	v_cvt_pk_bf16_f32 v98, v159, v111
	v_cvt_pk_bf16_f32 v99, v165, v166
	v_cvt_pk_bf16_f32 v100, v167, v168
	v_cvt_pk_bf16_f32 v101, v169, v170
	s_waitcnt lgkmcnt(13)
	v_mfma_f32_32x32x16_bf16 v[0:15], v[102:105], v[64:67], v[0:15]
	ds_read_b128 v[102:105], v96 offset:35840
	ds_read_b128 v[206:209], v96 offset:37888
	ds_read_b128 v[238:241], v96 offset:38912
	ds_read_b128 v[242:245], v96 offset:39936
	s_waitcnt lgkmcnt(9)
	v_mfma_f32_32x32x16_bf16 v[48:63], v[234:237], v[98:101], v[48:63]
	ds_read_b128 v[234:237], v96 offset:36864
	s_waitcnt lgkmcnt(9)
	v_mfma_f32_32x32x16_bf16 v[32:47], v[68:71], v[98:101], v[32:47]
	s_waitcnt lgkmcnt(8)
	v_mfma_f32_32x32x16_bf16 v[16:31], v[72:75], v[98:101], v[16:31]
	s_waitcnt lgkmcnt(7)
	v_mfma_f32_32x32x16_bf16 v[0:15], v[76:79], v[98:101], v[0:15]
	ds_read_b128 v[98:101], v96 offset:34816
	v_lshl_add_u64 v[160:161], v[160:161], 0, s[26:27]
	v_lshl_add_u64 v[162:163], v[162:163], 0, s[28:29]
	s_cmp_eq_u32 s5, 34
	s_cbranch_scc1 .Lmy_exit
	s_mov_b32 s2, s5
	s_branch .LBB0_784
.Lmy_exit:
	s_waitcnt lgkmcnt(0)
	v_max_f32_e32 v111, v219, v219
	v_max_f32_e32 v159, v218, v218
	v_max_f32_e32 v111, v159, v111
	v_max3_f32 v111, v111, v220, v221
	v_max3_f32 v111, v111, v222, v223
	v_max3_f32 v111, v111, v224, v225
	v_max3_f32 v111, v111, v226, v227
	v_max3_f32 v111, v111, v228, v229
	v_max3_f32 v111, v111, v230, v231
	v_max3_f32 v111, v111, v232, v233
	v_mov_b32_e32 v159, v111
	s_nop 1
	v_permlane32_swap_b32_e32 v111, v159
	v_max_f32_e32 v159, v159, v159
	v_max_f32_e32 v111, v111, v111
	v_max_f32_e32 v111, v111, v159
	v_mul_f32_e32 v111, 0x3dd53b94, v111
	v_cmp_le_f32_e32 vcc, v111, v110
	s_cmp_eq_u64 vcc, exec
	s_cbranch_scc1 .Lmy_x790
	v_max_f32_e32 v110, v111, v111
	v_max_f32_e32 v111, v80, v80
	v_max_f32_e32 v111, v111, v110
	v_sub_f32_e32 v80, v80, v111
	v_exp_f32_e32 v80, v80
	v_xor_b32_e32 v110, 0x80000000, v111
	v_mul_f32_e32 v81, v81, v80
	v_pk_mul_f32 v[62:63], v[62:63], v[80:81] op_sel_hi:[1,0]
	v_pk_mul_f32 v[60:61], v[60:61], v[80:81] op_sel_hi:[1,0]
	v_pk_mul_f32 v[58:59], v[58:59], v[80:81] op_sel_hi:[1,0]
	v_pk_mul_f32 v[56:57], v[56:57], v[80:81] op_sel_hi:[1,0]
	v_pk_mul_f32 v[54:55], v[54:55], v[80:81] op_sel_hi:[1,0]
	v_pk_mul_f32 v[52:53], v[52:53], v[80:81] op_sel_hi:[1,0]
	v_pk_mul_f32 v[50:51], v[50:51], v[80:81] op_sel_hi:[1,0]
	v_pk_mul_f32 v[48:49], v[48:49], v[80:81] op_sel_hi:[1,0]
	v_pk_mul_f32 v[46:47], v[46:47], v[80:81] op_sel_hi:[1,0]
	v_pk_mul_f32 v[44:45], v[44:45], v[80:81] op_sel_hi:[1,0]
	v_pk_mul_f32 v[42:43], v[42:43], v[80:81] op_sel_hi:[1,0]
	v_pk_mul_f32 v[40:41], v[40:41], v[80:81] op_sel_hi:[1,0]
	v_pk_mul_f32 v[38:39], v[38:39], v[80:81] op_sel_hi:[1,0]
	v_pk_mul_f32 v[36:37], v[36:37], v[80:81] op_sel_hi:[1,0]
	v_pk_mul_f32 v[34:35], v[34:35], v[80:81] op_sel_hi:[1,0]
	v_pk_mul_f32 v[32:33], v[32:33], v[80:81] op_sel_hi:[1,0]
	v_pk_mul_f32 v[30:31], v[30:31], v[80:81] op_sel_hi:[1,0]
	v_pk_mul_f32 v[28:29], v[28:29], v[80:81] op_sel_hi:[1,0]
	v_pk_mul_f32 v[26:27], v[26:27], v[80:81] op_sel_hi:[1,0]
	v_pk_mul_f32 v[24:25], v[24:25], v[80:81] op_sel_hi:[1,0]
	v_pk_mul_f32 v[22:23], v[22:23], v[80:81] op_sel_hi:[1,0]
	v_pk_mul_f32 v[20:21], v[20:21], v[80:81] op_sel_hi:[1,0]
	v_pk_mul_f32 v[18:19], v[18:19], v[80:81] op_sel_hi:[1,0]
	v_pk_mul_f32 v[16:17], v[16:17], v[80:81] op_sel_hi:[1,0]
	v_pk_mul_f32 v[14:15], v[14:15], v[80:81] op_sel_hi:[1,0]
	v_pk_mul_f32 v[12:13], v[12:13], v[80:81] op_sel_hi:[1,0]
	v_pk_mul_f32 v[10:11], v[10:11], v[80:81] op_sel_hi:[1,0]
	v_pk_mul_f32 v[8:9], v[8:9], v[80:81] op_sel_hi:[1,0]
	v_pk_mul_f32 v[6:7], v[6:7], v[80:81] op_sel_hi:[1,0]
	v_pk_mul_f32 v[4:5], v[4:5], v[80:81] op_sel_hi:[1,0]
	v_pk_mul_f32 v[2:3], v[2:3], v[80:81] op_sel_hi:[1,0]
	v_pk_mul_f32 v[0:1], v[0:1], v[80:81] op_sel_hi:[1,0]
	v_mov_b32_e32 v80, v111
	s_branch .Lmy_x791

.Lmy_x791:
	v_fmamk_f32 v218, v218, 0x3dd53b94, v110
	v_exp_f32_e32 v218, v218
	v_fmamk_f32 v219, v219, 0x3dd53b94, v110
	v_exp_f32_e32 v219, v219
	v_fmamk_f32 v220, v220, 0x3dd53b94, v110
	v_exp_f32_e32 v220, v220
	v_fmamk_f32 v221, v221, 0x3dd53b94, v110
	v_exp_f32_e32 v221, v221
	v_fmamk_f32 v222, v222, 0x3dd53b94, v110
	v_add_f32_e32 v111, 0, v218
	v_exp_f32_e32 v222, v222
	v_fmamk_f32 v223, v223, 0x3dd53b94, v110
	v_add_f32_e32 v111, v219, v111
	v_exp_f32_e32 v223, v223
	v_fmamk_f32 v224, v224, 0x3dd53b94, v110
	v_add_f32_e32 v111, v220, v111
	v_exp_f32_e32 v224, v224
	v_fmamk_f32 v225, v225, 0x3dd53b94, v110
	v_add_f32_e32 v111, v221, v111
	v_exp_f32_e32 v225, v225
	v_fmamk_f32 v226, v226, 0x3dd53b94, v110
	v_add_f32_e32 v111, v222, v111
	v_exp_f32_e32 v159, v226
	v_add_f32_e32 v111, v223, v111
	v_add_f32_e32 v111, v224, v111
	v_add_f32_e32 v111, v225, v111
	v_fmamk_f32 v227, v227, 0x3dd53b94, v110
	v_add_f32_e32 v226, v159, v111
	v_exp_f32_e32 v111, v227
	v_fmamk_f32 v227, v228, 0x3dd53b94, v110
	v_exp_f32_e32 v165, v227
	v_fmamk_f32 v227, v229, 0x3dd53b94, v110
	v_exp_f32_e32 v166, v227
	v_fmamk_f32 v227, v230, 0x3dd53b94, v110
	v_exp_f32_e32 v167, v227
	v_fmamk_f32 v227, v231, 0x3dd53b94, v110
	v_add_f32_e32 v226, v111, v226
	v_exp_f32_e32 v168, v227
	v_fmamk_f32 v227, v232, 0x3dd53b94, v110
	v_add_f32_e32 v226, v165, v226
	v_exp_f32_e32 v169, v227
	v_fmac_f32_e32 v110, 0x3dd53b94, v233
	v_add_f32_e32 v226, v166, v226
	v_exp_f32_e32 v110, v110
	v_add_f32_e32 v226, v167, v226
	v_add_f32_e32 v226, v168, v226
	v_add_f32_e32 v226, v169, v226
	v_add_f32_e32 v226, v110, v226
	v_cvt_pk_bf16_f32 v218, v218, v219
	v_cvt_pk_bf16_f32 v219, v220, v221
	v_cvt_pk_bf16_f32 v220, v222, v223
	v_cvt_pk_bf16_f32 v221, v224, v225
	v_mov_b32_e32 v227, v226
	s_nop 1
	v_permlane32_swap_b32_e32 v226, v227
	v_add_f32_e32 v226, v226, v227
	v_add_f32_e32 v81, v81, v226
	v_mfma_f32_32x32x16_bf16 v[48:63], v[148:151], v[218:221], v[48:63]
	v_mfma_f32_32x32x16_bf16 v[32:47], v[106:109], v[218:221], v[32:47]
	v_mfma_f32_32x32x16_bf16 v[16:31], v[98:101], v[218:221], v[16:31]
	v_cvt_pk_bf16_f32 v98, v159, v111
	v_cvt_pk_bf16_f32 v99, v165, v166
	v_cvt_pk_bf16_f32 v100, v167, v168
	v_cvt_pk_bf16_f32 v101, v169, v110
	v_mfma_f32_32x32x16_bf16 v[0:15], v[102:105], v[218:221], v[0:15]
	v_mfma_f32_32x32x16_bf16 v[48:63], v[234:237], v[98:101], v[48:63]
	v_mfma_f32_32x32x16_bf16 v[32:47], v[206:209], v[98:101], v[32:47]
	v_mfma_f32_32x32x16_bf16 v[16:31], v[238:241], v[98:101], v[16:31]
	v_mfma_f32_32x32x16_bf16 v[0:15], v[242:245], v[98:101], v[0:15]
.LBB0_793:
	s_nop 0
	s_and_b32 s2, s4, 0x7f
	s_lshl_b32 s3, s2, 3
	v_readlane_b32 s5, v250, 0
	s_add_i32 s3, s3, s5
	v_mov_b32_e32 v64, 0x4400
	v_mad_u64_u32 v[134:135], s[6:7], s3, v64, v[154:155]
	s_cmpk_gt_u32 s4, 0x7f
	s_mov_b64 s[8:9], -1
	s_cbranch_scc0 .LBB0_801
	v_readlane_b32 s6, v250, 15
	v_readlane_b32 s7, v250, 16
	s_andn2_b64 vcc, exec, s[6:7]
	s_cbranch_vccnz .LBB0_800
	s_lshl_b32 s2, s2, 6
	v_readlane_b32 s3, v252, 21
	s_add_u32 s8, s3, s2
	v_readlane_b32 s2, v252, 22
	s_addc_u32 s9, s2, 0
	s_mov_b32 s2, 0x100001
	s_branch .LBB0_797
